# fix_phase loop hand-rewritten: one index decode, all 14 loads of an item issued together, approximate reciprocal
# speedup vs baseline: 1.0045x; 1.0045x over previous
; __device__ __forceinline__ int otid(int wv) { int t; asm volatile("v_mbcnt_lo_u32_b32 %0, -1, 0\n\tv_mbcnt_hi_u32_b32 %0, -1, %0\n\tv_lshl_add_u32 %0, %1, 6, %0" : "=&v"(t) : "s"(wv)); return t; }
; __device__ void fix_phase(int wv, const Params& p, int li) {
;     const float* edge = (const float*)(p.ws + WS_EDGE); const float* cw = (const float*)(p.ws + WS_CW) + (size_t)li * 4 * NUP; bf16_t* act = (bf16_t*)(p.ws + WS_ACT);
;     const int total = 1024 * (FFD / 4);
;     const int tid = otid(wv);
;     for (int idx = blockIdx.x * NTHR + tid; idx < total; idx += gridDim.x * NTHR) {
;         const int e = idx / (FFD / 4), c = (idx % (FFD / 4)) * 4; const int band = e >> 1, hi = e & 1; const int R = band * 64 + (hi ? 63 : 0);
;         const int ca = (c >> 7) * 256 + (c & 127), cg_ = ca + 128;
;         const bool seqstart = (R == 0 || R == 8192 || R == 16384), seqend = (R == 8191 || R == 16383 || R == 32767);
;         const float* ep = edge + (size_t)band * 4 * NUP;
;         f32x4 pa, pg, ua, ug, na, ng; const f32x4 zero = {0, 0, 0, 0};
;         if (!hi) { pa = seqstart ? zero : *(const f32x4*)(ep - NUP + ca); pg = seqstart ? zero : *(const f32x4*)(ep - NUP + cg_);
;             ua = *(const f32x4*)(ep + ca); ug = *(const f32x4*)(ep + cg_); na = *(const f32x4*)(ep + NUP + ca); ng = *(const f32x4*)(ep + NUP + cg_); }
;         else { pa = *(const f32x4*)(ep + 2 * NUP + ca); pg = *(const f32x4*)(ep + 2 * NUP + cg_); ua = *(const f32x4*)(ep + 3 * NUP + ca); ug = *(const f32x4*)(ep + 3 * NUP + cg_);
;             na = seqend ? zero : *(const f32x4*)(ep + 4 * NUP + ca); ng = seqend ? zero : *(const f32x4*)(ep + 4 * NUP + cg_); }
;         const f32x4 a = *(const f32x4*)(cw + ca) * pa + *(const f32x4*)(cw + NUP + ca) * ua + *(const f32x4*)(cw + 2 * NUP + ca) * na + *(const f32x4*)(cw + 3 * NUP + ca);
;         const f32x4 g = *(const f32x4*)(cw + cg_) * pg + *(const f32x4*)(cw + NUP + cg_) * ug + *(const f32x4*)(cw + 2 * NUP + cg_) * ng + *(const f32x4*)(cw + 3 * NUP + cg_);
;         float o[4];
; #pragma unroll
;         for (int j = 0; j < 4; ++j) o[j] = a[j] * g[j] / (1.0f + __expf(-g[j]));
;         u32x2 wv; wv.x = cvt_pk_bf16(o[0], o[1]); wv.y = cvt_pk_bf16(o[2], o[3]);
;         *(u32x2*)(act + (size_t)R * FFD + c) = wv;
;     }
.Lfix_loop:
	v_lshrrev_b32_e32 v6, 6, v36
	v_mov_b32_e32 v7, 0xba2e8ba3
	v_mul_hi_u32 v2, v6, v7
	v_lshrrev_b32_e32 v2, 3, v2
	v_mul_u32_u24_e32 v6, 0x2c0, v2
	v_sub_u32_e32 v3, v36, v6
	v_lshrrev_b32_e32 v4, 1, v2
	v_and_b32_e32 v5, 1, v2
	v_lshrrev_b32_e32 v6, 5, v3
	v_and_b32_e32 v7, 31, v3
	v_lshlrev_b32_e32 v7, 2, v7
	v_lshl_add_u32 v6, v6, 8, v7
	v_lshlrev_b32_e32 v15, 2, v6
	v_cmp_eq_u32_e64 s[8:9], 1, v5
	v_cmp_eq_u32_e64 s[10:11], 0, v4
	s_movk_i32 s36, 0x80
	v_cmp_eq_u32_e64 s[12:13], s36, v4
	s_movk_i32 s36, 0x100
	v_cmp_eq_u32_e64 s[14:15], s36, v4
	s_or_b64 s[10:11], s[10:11], s[12:13]
	s_or_b64 s[10:11], s[10:11], s[14:15]
	v_cndmask_b32_e64 v7, 1, 0, s[10:11]
	v_or_b32_e32 v7, v7, v5
	s_movk_i32 s36, 0x7f
	v_cmp_eq_u32_e64 s[10:11], s36, v4
	s_movk_i32 s36, 0xff
	v_cmp_eq_u32_e64 s[12:13], s36, v4
	s_movk_i32 s36, 0x1ff
	v_cmp_eq_u32_e64 s[14:15], s36, v4
	s_or_b64 s[10:11], s[10:11], s[12:13]
	s_or_b64 s[10:11], s[10:11], s[14:15]
	v_cndmask_b32_e64 v8, 1, 0, s[10:11]
	v_xor_b32_e32 v6, 1, v5
	v_or_b32_e32 v8, v8, v6
	v_cvt_f32_u32_e32 v16, v7
	v_cvt_f32_u32_e32 v17, v8
	v_sub_u32_e32 v6, 0, v7
	v_cndmask_b32_e64 v9, v6, 2, s[8:9]
	v_mul_u32_u24_e32 v10, 3, v5
	v_add_u32_e32 v6, 3, v8
	v_cndmask_b32_e64 v11, 1, v6, s[8:9]
	v_lshlrev_b32_e32 v6, 2, v4
	v_add_u32_e32 v7, v6, v9
	v_mul_u32_u24_e32 v7, 0x5800, v7
	v_add_u32_e32 v12, v7, v15
	v_add_u32_e32 v7, v6, v10
	v_mul_u32_u24_e32 v7, 0x5800, v7
	v_add_u32_e32 v13, v7, v15
	v_add_u32_e32 v7, v6, v11
	v_mul_u32_u24_e32 v7, 0x5800, v7
	v_add_u32_e32 v14, v7, v15
	global_load_dwordx4 v[20:23], v12, s[40:41]
	global_load_dwordx4 v[24:27], v12, s[40:41] offset:512
	global_load_dwordx4 v[28:31], v13, s[40:41]
	global_load_dwordx4 v[32:35], v13, s[40:41] offset:512
	global_load_dwordx4 v[40:43], v14, s[40:41]
	global_load_dwordx4 v[44:47], v14, s[40:41] offset:512
	global_load_dwordx4 v[48:51], v15, s[92:93]
	global_load_dwordx4 v[52:55], v15, s[92:93] offset:512
	global_load_dwordx4 v[56:59], v15, s[96:97]
	global_load_dwordx4 v[60:63], v15, s[96:97] offset:512
	global_load_dwordx4 v[64:67], v15, s[20:21]
	global_load_dwordx4 v[68:71], v15, s[20:21] offset:512
	global_load_dwordx4 v[72:75], v15, s[84:85]
	global_load_dwordx4 v[76:79], v15, s[84:85] offset:512
	v_mul_u32_u24_e32 v6, 63, v5
	v_lshl_add_u32 v6, v4, 6, v6
	v_mul_u32_u24_e32 v37, 0x1600, v6
	v_lshl_add_u32 v37, v3, 3, v37
	s_waitcnt vmcnt(0)
	v_pk_mul_f32 v[48:49], v[48:49], v[16:17] op_sel_hi:[1,0]
	v_pk_mul_f32 v[50:51], v[50:51], v[16:17] op_sel_hi:[1,0]
	v_pk_mul_f32 v[52:53], v[52:53], v[16:17] op_sel_hi:[1,0]
	v_pk_mul_f32 v[54:55], v[54:55], v[16:17] op_sel_hi:[1,0]
	v_pk_mul_f32 v[64:65], v[64:65], v[16:17] op_sel:[0,1] op_sel_hi:[1,1]
	v_pk_mul_f32 v[66:67], v[66:67], v[16:17] op_sel:[0,1] op_sel_hi:[1,1]
	v_pk_mul_f32 v[68:69], v[68:69], v[16:17] op_sel:[0,1] op_sel_hi:[1,1]
	v_pk_mul_f32 v[70:71], v[70:71], v[16:17] op_sel:[0,1] op_sel_hi:[1,1]
	v_pk_mul_f32 v[20:21], v[48:49], v[20:21]
	v_pk_fma_f32 v[20:21], v[56:57], v[28:29], v[20:21]
	v_pk_fma_f32 v[20:21], v[64:65], v[40:41], v[20:21]
	v_pk_add_f32 v[20:21], v[20:21], v[72:73]
	v_pk_mul_f32 v[22:23], v[50:51], v[22:23]
	v_pk_fma_f32 v[22:23], v[58:59], v[30:31], v[22:23]
	v_pk_fma_f32 v[22:23], v[66:67], v[42:43], v[22:23]
	v_pk_add_f32 v[22:23], v[22:23], v[74:75]
	v_pk_mul_f32 v[24:25], v[52:53], v[24:25]
	v_pk_fma_f32 v[24:25], v[60:61], v[32:33], v[24:25]
	v_pk_fma_f32 v[24:25], v[68:69], v[44:45], v[24:25]
	v_pk_add_f32 v[24:25], v[24:25], v[76:77]
	v_pk_mul_f32 v[26:27], v[54:55], v[26:27]
	v_pk_fma_f32 v[26:27], v[62:63], v[34:35], v[26:27]
	v_pk_fma_f32 v[26:27], v[70:71], v[46:47], v[26:27]
	v_pk_add_f32 v[26:27], v[26:27], v[78:79]
	v_mul_f32_e32 v32, 0xbfb8aa3b, v24
	v_mul_f32_e32 v33, 0xbfb8aa3b, v25
	v_mul_f32_e32 v34, 0xbfb8aa3b, v26
	v_mul_f32_e32 v35, 0xbfb8aa3b, v27
	v_exp_f32_e32 v32, v32
	v_exp_f32_e32 v33, v33
	v_exp_f32_e32 v34, v34
	v_exp_f32_e32 v35, v35
	v_add_f32_e32 v32, 1.0, v32
	v_add_f32_e32 v33, 1.0, v33
	v_add_f32_e32 v34, 1.0, v34
	v_add_f32_e32 v35, 1.0, v35
	v_rcp_f32_e32 v32, v32
	v_rcp_f32_e32 v33, v33
	v_rcp_f32_e32 v34, v34
	v_rcp_f32_e32 v35, v35
	s_nop 0
	v_pk_mul_f32 v[24:25], v[24:25], v[32:33]
	v_pk_mul_f32 v[26:27], v[26:27], v[34:35]
	v_pk_mul_f32 v[20:21], v[20:21], v[24:25]
	v_pk_mul_f32 v[22:23], v[22:23], v[26:27]
	v_cvt_pk_bf16_f32 v28, v20, v21
	v_cvt_pk_bf16_f32 v29, v22, v23
	global_store_dwordx2 v37, v[28:29], s[76:77]
	v_add_u32_e32 v36, s44, v36
	v_cmp_gt_i32_e32 vcc, 0xb0000, v36
	s_and_b64 exec, exec, vcc
	s_cbranch_execnz .Lfix_loop
